# in-proj phase runs 240 GEMM WGs + 16 conversion helpers (last round on half the chip clocks higher); conversion split moved to W_in+W_out | rest; conversion LDS reads batched
# speedup vs baseline: 1.0114x; 1.0049x over previous
.LBB0_57:
	ds_write_b128 v144, v[70:73]
	ds_write_b128 v144, v[66:69] offset:1088
	ds_write_b128 v144, v[78:81] offset:2176
	ds_write_b128 v144, v[74:77] offset:3264
	ds_write_b128 v144, v[86:89] offset:4352
	ds_write_b128 v144, v[82:85] offset:5440
	ds_write_b128 v144, v[94:97] offset:6528
	ds_write_b128 v144, v[90:93] offset:7616
	ds_write_b128 v144, v[110:113] offset:8704
	ds_write_b128 v144, v[106:109] offset:9792
	ds_write_b128 v144, v[102:105] offset:10880
	ds_write_b128 v144, v[98:101] offset:11968
	ds_write_b128 v144, v[118:121] offset:13056
	ds_write_b128 v144, v[114:117] offset:14144
	ds_write_b128 v144, v[126:129] offset:15232
	ds_write_b128 v144, v[122:125] offset:16320
	s_waitcnt lgkmcnt(0)
	ds_read2_b32 v[156:157], v143 offset1:68
	ds_read2_b32 v[158:159], v143 offset0:136 offset1:204
	ds_read2_b32 v[160:161], v145 offset0:16 offset1:84
	ds_read2_b32 v[162:163], v145 offset0:152 offset1:220
	ds_read2_b32 v[164:165], v143 offset0:8 offset1:76
	ds_read2_b32 v[166:167], v143 offset0:144 offset1:212
	ds_read2_b32 v[168:169], v145 offset0:24 offset1:92
	ds_read2_b32 v[170:171], v145 offset0:160 offset1:228
	v_add_u32_e32 v135, s6, v136
	s_waitcnt lgkmcnt(4)
	v_cvt_pk_bf16_f32 v148, v156, v157
	v_cvt_pk_bf16_f32 v149, v158, v159
	v_cvt_pk_bf16_f32 v150, v160, v161
	v_cvt_pk_bf16_f32 v151, v162, v163
	ds_read2_b32 v[156:157], v143 offset0:16 offset1:84
	ds_read2_b32 v[158:159], v143 offset0:152 offset1:220
	ds_read2_b32 v[160:161], v145 offset0:32 offset1:100
	ds_read2_b32 v[162:163], v145 offset0:168 offset1:236
	v_mad_i64_i32 v[152:153], s[50:51], s11, v135, 0
	s_ashr_i32 s47, s46, 31
	v_lshl_add_u64 v[152:153], v[152:153], 1, s[44:45]
	s_lshl_b64 s[50:51], s[46:47], 1
	v_lshl_add_u64 v[152:153], v[152:153], 0, s[50:51]
	v_mov_b32_e32 v135, v131
	v_lshl_add_u64 v[152:153], v[152:153], 0, v[134:135]
	global_store_dwordx4 v[152:153], v[148:151], off nt
	s_nop 1
	s_cmp_lt_i32 s54, 0
	s_waitcnt lgkmcnt(4)
	v_cvt_pk_bf16_f32 v148, v164, v165
	v_cvt_pk_bf16_f32 v149, v166, v167
	v_cvt_pk_bf16_f32 v150, v168, v169
	v_cvt_pk_bf16_f32 v151, v170, v171
	ds_read2_b32 v[164:165], v143 offset0:24 offset1:92
	ds_read2_b32 v[166:167], v143 offset0:160 offset1:228
	ds_read2_b32 v[168:169], v145 offset0:40 offset1:108
	ds_read2_b32 v[170:171], v145 offset0:176 offset1:244
	v_add_u32_e32 v152, s6, v1
	v_mad_i64_i32 v[152:153], s[58:59], s11, v152, 0
	v_lshl_add_u64 v[152:153], v[152:153], 1, s[44:45]
	v_lshl_add_u64 v[152:153], v[152:153], 0, s[50:51]
	v_lshl_add_u64 v[152:153], v[152:153], 0, v[134:135]
	global_store_dwordx4 v[152:153], v[148:151], off nt
	s_nop 1
	s_nop 0
	v_add_u32_e32 v151, s6, v137
	v_mad_i64_i32 v[154:155], s[58:59], s11, v151, 0
	v_lshl_add_u64 v[154:155], v[154:155], 1, s[44:45]
	v_lshl_add_u64 v[154:155], v[154:155], 0, s[50:51]
	s_waitcnt lgkmcnt(4)
	v_cvt_pk_bf16_f32 v148, v156, v157
	v_cvt_pk_bf16_f32 v149, v158, v159
	v_cvt_pk_bf16_f32 v150, v160, v161
	v_cvt_pk_bf16_f32 v151, v162, v163
	ds_read2_b32 v[156:157], v143 offset0:32 offset1:100
	ds_read2_b32 v[158:159], v143 offset0:168 offset1:236
	ds_read2_b32 v[160:161], v145 offset0:48 offset1:116
	ds_read2_b32 v[162:163], v145 offset0:184 offset1:252
	v_lshl_add_u64 v[154:155], v[154:155], 0, v[134:135]
	global_store_dwordx4 v[154:155], v[148:151], off nt
	s_nop 1
	s_nop 0
	v_add_u32_e32 v151, s6, v138
	v_mad_i64_i32 v[154:155], s[58:59], s11, v151, 0
	v_lshl_add_u64 v[154:155], v[154:155], 1, s[44:45]
	v_lshl_add_u64 v[154:155], v[154:155], 0, s[50:51]
	s_waitcnt lgkmcnt(4)
	v_cvt_pk_bf16_f32 v148, v164, v165
	v_cvt_pk_bf16_f32 v149, v166, v167
	v_cvt_pk_bf16_f32 v150, v168, v169
	v_cvt_pk_bf16_f32 v151, v170, v171
	ds_read2_b32 v[164:165], v143 offset0:40 offset1:108
	ds_read2_b32 v[166:167], v143 offset0:176 offset1:244
	ds_read2_b32 v[168:169], v145 offset0:56 offset1:124
	ds_read2_b32 v[170:171], v146 offset0:64 offset1:132
	v_lshl_add_u64 v[154:155], v[154:155], 0, v[134:135]
	global_store_dwordx4 v[154:155], v[148:151], off nt
	s_nop 1
	s_nop 0
	v_add_u32_e32 v151, s6, v139
	v_mad_i64_i32 v[154:155], s[58:59], s11, v151, 0
	v_lshl_add_u64 v[154:155], v[154:155], 1, s[44:45]
	v_lshl_add_u64 v[154:155], v[154:155], 0, s[50:51]
	s_waitcnt lgkmcnt(4)
	v_cvt_pk_bf16_f32 v148, v156, v157
	v_cvt_pk_bf16_f32 v149, v158, v159
	v_cvt_pk_bf16_f32 v150, v160, v161
	v_cvt_pk_bf16_f32 v151, v162, v163
	ds_read2_b32 v[156:157], v143 offset0:48 offset1:116
	ds_read2_b32 v[158:159], v143 offset0:184 offset1:252
	ds_read2_b32 v[160:161], v145 offset0:64 offset1:132
	ds_read2_b32 v[162:163], v146 offset0:72 offset1:140
	v_lshl_add_u64 v[154:155], v[154:155], 0, v[134:135]
	global_store_dwordx4 v[154:155], v[148:151], off nt
	s_nop 1
	s_nop 0
	v_add_u32_e32 v151, s6, v140
	v_mad_i64_i32 v[154:155], s[58:59], s11, v151, 0
	v_lshl_add_u64 v[154:155], v[154:155], 1, s[44:45]
	v_lshl_add_u64 v[154:155], v[154:155], 0, s[50:51]
	s_waitcnt lgkmcnt(4)
	v_cvt_pk_bf16_f32 v148, v164, v165
	v_cvt_pk_bf16_f32 v149, v166, v167
	v_cvt_pk_bf16_f32 v150, v168, v169
	v_cvt_pk_bf16_f32 v151, v170, v171
	ds_read2_b32 v[164:165], v143 offset0:56 offset1:124
	ds_read2_b32 v[166:167], v147 offset0:64 offset1:132
	ds_read2_b32 v[168:169], v145 offset0:72 offset1:140
	ds_read2_b32 v[170:171], v146 offset0:80 offset1:148
	v_lshl_add_u64 v[154:155], v[154:155], 0, v[134:135]
	global_store_dwordx4 v[154:155], v[148:151], off nt
	s_nop 1
	s_nop 0
	v_add_u32_e32 v151, s6, v141
	v_mad_i64_i32 v[154:155], s[58:59], s11, v151, 0
	v_lshl_add_u64 v[154:155], v[154:155], 1, s[44:45]
	v_lshl_add_u64 v[154:155], v[154:155], 0, s[50:51]
	s_waitcnt lgkmcnt(4)
	v_cvt_pk_bf16_f32 v148, v156, v157
	v_cvt_pk_bf16_f32 v149, v158, v159
	v_cvt_pk_bf16_f32 v150, v160, v161
	v_cvt_pk_bf16_f32 v151, v162, v163
	v_lshl_add_u64 v[154:155], v[154:155], 0, v[134:135]
	global_store_dwordx4 v[154:155], v[148:151], off nt
	s_nop 1
	s_nop 0
	v_add_u32_e32 v145, s6, v142
	v_mad_i64_i32 v[152:153], s[58:59], s11, v145, 0
	v_lshl_add_u64 v[152:153], v[152:153], 1, s[44:45]
	v_lshl_add_u64 v[152:153], v[152:153], 0, s[50:51]
	v_lshl_add_u64 v[134:135], v[152:153], 0, v[134:135]
	s_waitcnt lgkmcnt(0)
	v_cvt_pk_bf16_f32 v148, v164, v165
	v_cvt_pk_bf16_f32 v149, v166, v167
	v_cvt_pk_bf16_f32 v150, v168, v169
	v_cvt_pk_bf16_f32 v151, v170, v171
	global_store_dwordx4 v[134:135], v[148:151], off nt
	s_waitcnt lgkmcnt(0)
	s_cselect_b64 s[50:51], -1, 0

.LBB0_76:
	s_waitcnt vmcnt(15)
	ds_write_b128 v144, v[2:5]
	s_waitcnt vmcnt(14)
	ds_write_b128 v144, v[6:9] offset:1088
	s_waitcnt vmcnt(13)
	ds_write_b128 v144, v[10:13] offset:2176
	s_waitcnt vmcnt(12)
	ds_write_b128 v144, v[14:17] offset:3264
	s_waitcnt vmcnt(11)
	ds_write_b128 v144, v[18:21] offset:4352
	s_waitcnt vmcnt(10)
	ds_write_b128 v144, v[22:25] offset:5440
	s_waitcnt vmcnt(9)
	ds_write_b128 v144, v[26:29] offset:6528
	s_waitcnt vmcnt(8)
	ds_write_b128 v144, v[30:33] offset:7616
	s_waitcnt vmcnt(7)
	ds_write_b128 v144, v[34:37] offset:8704
	s_waitcnt vmcnt(6)
	ds_write_b128 v144, v[38:41] offset:9792
	s_waitcnt vmcnt(5)
	ds_write_b128 v144, v[42:45] offset:10880
	s_waitcnt vmcnt(4)
	ds_write_b128 v144, v[46:49] offset:11968
	s_waitcnt vmcnt(3)
	ds_write_b128 v144, v[50:53] offset:13056
	s_waitcnt vmcnt(2)
	ds_write_b128 v144, v[54:57] offset:14144
	s_waitcnt vmcnt(1)
	ds_write_b128 v144, v[58:61] offset:15232
	s_waitcnt vmcnt(0)
	ds_write_b128 v144, v[62:65] offset:16320
	s_waitcnt lgkmcnt(0)
	v_add_u32_e32 v172, 0x400, v143
	v_add_u32_e32 v173, 0x600, v143
	v_add_u32_e32 v174, 0x200, v143
	ds_read2_b32 v[156:157], v143 offset1:68
	ds_read2_b32 v[158:159], v143 offset0:136 offset1:204
	ds_read2_b32 v[160:161], v172 offset0:16 offset1:84
	ds_read2_b32 v[162:163], v172 offset0:152 offset1:220
	ds_read2_b32 v[164:165], v143 offset0:8 offset1:76
	ds_read2_b32 v[166:167], v143 offset0:144 offset1:212
	ds_read2_b32 v[168:169], v172 offset0:24 offset1:92
	ds_read2_b32 v[170:171], v172 offset0:160 offset1:228
	v_add_u32_e32 v145, 0x400, v143
	s_waitcnt lgkmcnt(4)
	v_cvt_pk_bf16_f32 v146, v156, v157
	v_cvt_pk_bf16_f32 v147, v158, v159
	v_cvt_pk_bf16_f32 v148, v160, v161
	v_cvt_pk_bf16_f32 v149, v162, v163
	ds_read2_b32 v[156:157], v143 offset0:16 offset1:84
	ds_read2_b32 v[158:159], v143 offset0:152 offset1:220
	ds_read2_b32 v[160:161], v172 offset0:32 offset1:100
	ds_read2_b32 v[162:163], v172 offset0:168 offset1:236
	v_or_b32_e32 v134, s48, v136
	v_mad_u64_u32 v[134:135], s[50:51], v134, s56, 0
	s_mov_b32 s17, s7
	v_lshl_add_u64 v[134:135], v[134:135], 1, s[12:13]
	s_lshl_b64 s[50:51], s[16:17], 1
	v_lshl_add_u64 v[150:151], v[134:135], 0, s[50:51]
	v_lshlrev_b32_e32 v134, 1, v132
	v_mov_b32_e32 v135, v131
	v_lshl_add_u64 v[150:151], v[150:151], 0, v[134:135]
	global_store_dwordx4 v[150:151], v[146:149], off nt
	s_nop 1
	s_cmp_lt_i32 s53, 0
	s_waitcnt lgkmcnt(4)
	v_cvt_pk_bf16_f32 v146, v164, v165
	v_cvt_pk_bf16_f32 v147, v166, v167
	v_cvt_pk_bf16_f32 v148, v168, v169
	v_cvt_pk_bf16_f32 v149, v170, v171
	ds_read2_b32 v[164:165], v143 offset0:24 offset1:92
	ds_read2_b32 v[166:167], v143 offset0:160 offset1:228
	ds_read2_b32 v[168:169], v172 offset0:40 offset1:108
	ds_read2_b32 v[170:171], v172 offset0:176 offset1:244
	v_or_b32_e32 v150, s48, v1
	v_mad_u64_u32 v[150:151], s[54:55], v150, s56, 0
	v_lshl_add_u64 v[150:151], v[150:151], 1, s[12:13]
	v_lshl_add_u64 v[150:151], v[150:151], 0, s[50:51]
	v_lshl_add_u64 v[150:151], v[150:151], 0, v[134:135]
	global_store_dwordx4 v[150:151], v[146:149], off nt
	s_nop 1
	s_nop 0
	v_or_b32_e32 v149, s48, v137
	v_mad_u64_u32 v[152:153], s[54:55], v149, s56, 0
	v_lshl_add_u64 v[152:153], v[152:153], 1, s[12:13]
	v_lshl_add_u64 v[152:153], v[152:153], 0, s[50:51]
	s_waitcnt lgkmcnt(4)
	v_cvt_pk_bf16_f32 v146, v156, v157
	v_cvt_pk_bf16_f32 v147, v158, v159
	v_cvt_pk_bf16_f32 v148, v160, v161
	v_cvt_pk_bf16_f32 v149, v162, v163
	ds_read2_b32 v[156:157], v143 offset0:32 offset1:100
	ds_read2_b32 v[158:159], v143 offset0:168 offset1:236
	ds_read2_b32 v[160:161], v172 offset0:48 offset1:116
	ds_read2_b32 v[162:163], v172 offset0:184 offset1:252
	v_lshl_add_u64 v[152:153], v[152:153], 0, v[134:135]
	global_store_dwordx4 v[152:153], v[146:149], off nt
	s_nop 1
	s_nop 0
	v_or_b32_e32 v149, s48, v138
	v_mad_u64_u32 v[152:153], s[54:55], v149, s56, 0
	v_lshl_add_u64 v[152:153], v[152:153], 1, s[12:13]
	v_lshl_add_u64 v[152:153], v[152:153], 0, s[50:51]
	s_waitcnt lgkmcnt(4)
	v_cvt_pk_bf16_f32 v146, v164, v165
	v_cvt_pk_bf16_f32 v147, v166, v167
	v_cvt_pk_bf16_f32 v148, v168, v169
	v_cvt_pk_bf16_f32 v149, v170, v171
	ds_read2_b32 v[164:165], v143 offset0:40 offset1:108
	ds_read2_b32 v[166:167], v143 offset0:176 offset1:244
	ds_read2_b32 v[168:169], v172 offset0:56 offset1:124
	ds_read2_b32 v[170:171], v173 offset0:64 offset1:132
	v_lshl_add_u64 v[152:153], v[152:153], 0, v[134:135]
	global_store_dwordx4 v[152:153], v[146:149], off nt
	s_nop 1
	s_nop 0
	v_or_b32_e32 v149, s48, v139
	v_mad_u64_u32 v[152:153], s[54:55], v149, s56, 0
	v_lshl_add_u64 v[152:153], v[152:153], 1, s[12:13]
	v_lshl_add_u64 v[152:153], v[152:153], 0, s[50:51]
	v_lshl_add_u64 v[152:153], v[152:153], 0, v[134:135]
	s_waitcnt lgkmcnt(4)
	v_cvt_pk_bf16_f32 v146, v156, v157
	v_cvt_pk_bf16_f32 v147, v158, v159
	v_cvt_pk_bf16_f32 v148, v160, v161
	v_cvt_pk_bf16_f32 v149, v162, v163
	ds_read2_b32 v[156:157], v143 offset0:48 offset1:116
	ds_read2_b32 v[158:159], v143 offset0:184 offset1:252
	ds_read2_b32 v[160:161], v172 offset0:64 offset1:132
	ds_read2_b32 v[162:163], v173 offset0:72 offset1:140
	global_store_dwordx4 v[152:153], v[146:149], off nt
	s_nop 1
	s_nop 0
	v_or_b32_e32 v147, s48, v140
	v_mad_u64_u32 v[154:155], s[54:55], v147, s56, 0
	v_lshl_add_u64 v[154:155], v[154:155], 1, s[12:13]
	v_add_u32_e32 v146, 0x600, v143
	v_lshl_add_u64 v[154:155], v[154:155], 0, s[50:51]
	s_waitcnt lgkmcnt(4)
	v_cvt_pk_bf16_f32 v148, v164, v165
	v_cvt_pk_bf16_f32 v149, v166, v167
	v_cvt_pk_bf16_f32 v150, v168, v169
	v_cvt_pk_bf16_f32 v151, v170, v171
	ds_read2_b32 v[164:165], v143 offset0:56 offset1:124
	ds_read2_b32 v[166:167], v174 offset0:64 offset1:132
	ds_read2_b32 v[168:169], v172 offset0:72 offset1:140
	ds_read2_b32 v[170:171], v173 offset0:80 offset1:148
	v_lshl_add_u64 v[154:155], v[154:155], 0, v[134:135]
	global_store_dwordx4 v[154:155], v[148:151], off nt
	s_nop 1
	v_add_u32_e32 v147, 0x200, v143
	v_or_b32_e32 v151, s48, v141
	v_mad_u64_u32 v[154:155], s[54:55], v151, s56, 0
	v_lshl_add_u64 v[154:155], v[154:155], 1, s[12:13]
	v_lshl_add_u64 v[154:155], v[154:155], 0, s[50:51]
	v_lshl_add_u64 v[154:155], v[154:155], 0, v[134:135]
	s_waitcnt lgkmcnt(4)
	v_cvt_pk_bf16_f32 v148, v156, v157
	v_cvt_pk_bf16_f32 v149, v158, v159
	v_cvt_pk_bf16_f32 v150, v160, v161
	v_cvt_pk_bf16_f32 v151, v162, v163
	global_store_dwordx4 v[154:155], v[148:151], off nt
	s_nop 1
	v_or_b32_e32 v154, s48, v142
	v_mad_u64_u32 v[154:155], s[54:55], v154, s56, 0
	v_lshl_add_u64 v[154:155], v[154:155], 1, s[12:13]
	v_lshl_add_u64 v[154:155], v[154:155], 0, s[50:51]
	s_waitcnt lgkmcnt(0)
	v_cvt_pk_bf16_f32 v148, v164, v165
	v_cvt_pk_bf16_f32 v149, v166, v167
	v_cvt_pk_bf16_f32 v150, v168, v169
	v_cvt_pk_bf16_f32 v151, v170, v171
	v_lshl_add_u64 v[152:153], v[154:155], 0, v[134:135]
	global_store_dwordx4 v[152:153], v[148:151], off nt
	s_waitcnt lgkmcnt(0)
	s_mov_b64 s[50:51], -1
	s_cbranch_scc1 .LBB0_58
	s_add_i32 s53, s49, 1
	s_cmp_lt_i32 s53, s52
	s_cbranch_scc1 .LBB0_83
	v_mov_b32_e32 v135, 0
	s_and_saveexec_b64 s[50:51], s[4:5]
	s_cbranch_execz .LBB0_82
	s_mov_b64 s[54:55], exec
	v_mbcnt_lo_u32_b32 v135, s54, 0
	v_mbcnt_hi_u32_b32 v135, s55, v135
	v_cmp_eq_u32_e32 vcc, 0, v135
	s_and_saveexec_b64 s[52:53], vcc
	s_cbranch_execz .LBB0_81
	s_bcnt1_i32_b64 s17, s[54:55]
	s_lshl_b32 s17, s17, 3
	v_mov_b32_e32 v148, s17
	global_atomic_add v148, v131, v148, s[14:15] offset:512 sc0

.LBB0_379:
	s_andn2_b64 vcc, exec, s[0:1]
	s_cbranch_vccnz .LBB0_767
	v_readlane_b32 s1, v255, 1
	s_nop 3
	s_cmpk_eq_i32 s1, 0xe0
	s_cselect_b32 s1, 0xf0, s1
	v_readlane_b32 s0, v253, 49
	s_nop 3
	s_cmp_eq_u32 s0, 3
	v_readlane_b32 s0, v252, 0
	s_nop 3
	s_cselect_b32 s58, s0, s1
	v_readlane_b32 s0, v253, 9
	v_readlane_b32 s1, v253, 10
	s_cmp_ge_i32 s0, s58
	s_mov_b64 s[0:1], -1
	s_cbranch_scc0 .LBB0_434
	s_waitcnt vmcnt(0)
	v_mov_b32_e32 v2, v0
	v_readlane_b32 s0, v253, 49
	v_readlane_b32 s1, v253, 50
	v_and_b32_e32 v68, 63, v2
	s_add_i32 s4, s0, 1
	v_readfirstlane_b32 s12, v2
	v_mov_b32_e32 v2, 0
	v_cmp_eq_u32_e64 s[38:39], 0, v68
	s_and_saveexec_b64 s[0:1], s[38:39]
	s_cbranch_execz .LBB0_385
	s_mov_b64 s[8:9], exec
	v_mbcnt_lo_u32_b32 v2, s8, 0
	v_mbcnt_hi_u32_b32 v2, s9, v2
	v_cmp_eq_u32_e32 vcc, 0, v2
	s_and_saveexec_b64 s[6:7], vcc
	s_cbranch_execz .LBB0_384
	s_lshl_b32 s10, s4, 6
	s_mov_b32 s11, s5
	s_lshl_b64 s[10:11], s[10:11], 2
	s_add_u32 s10, s26, s10
	s_addc_u32 s11, s27, s11
	s_bcnt1_i32_b64 s8, s[8:9]
	s_lshl_b32 s8, s8, 3
	v_mov_b32_e32 v3, s8
	global_atomic_add v3, v35, v3, s[10:11] offset:512 sc0

.LBB0_385:
	s_or_b64 exec, exec, s[0:1]
	v_readfirstlane_b32 s57, v2
	s_cmpk_gt_i32 s57, 0x13ff
	s_cselect_b64 s[6:7], -1, 0
	s_cmpk_lt_i32 s57, 0x1400
	s_cselect_b32 s15, s57, -1
	s_cmp_lt_i32 s15, 0
	s_cbranch_scc1 .LBB0_433
	s_cmpk_gt_u32 s15, 0xfff
	s_mov_b64 s[8:9], -1
	s_cbranch_scc0 .LBB0_395
	s_cmpk_gt_u32 s15, 0x13ff
	s_cbranch_scc0 .LBB0_392
	s_lshl_b64 s[44:45], s[4:5], 26
	s_lshl_b64 s[46:47], s[4:5], 25
	s_and_b64 vcc, exec, s[6:7]
	s_cbranch_vccz .LBB0_390
	s_add_u32 s10, s20, s44
	s_addc_u32 s11, s21, s45
	v_readlane_b32 s0, v252, 29
	s_add_u32 s0, s0, s46
	v_readlane_b32 s1, v252, 30
	s_addc_u32 s1, s1, s47
	s_mov_b64 s[8:9], 0

.LBB0_400:
	ds_write_b128 v145, v[72:75]
	ds_write_b128 v145, v[68:71] offset:1088
	ds_write_b128 v145, v[80:83] offset:2176
	ds_write_b128 v145, v[76:79] offset:3264
	ds_write_b128 v145, v[88:91] offset:4352
	ds_write_b128 v145, v[84:87] offset:5440
	ds_write_b128 v145, v[96:99] offset:6528
	ds_write_b128 v145, v[92:95] offset:7616
	ds_write_b128 v145, v[104:107] offset:8704
	ds_write_b128 v145, v[100:103] offset:9792
	ds_write_b128 v145, v[112:115] offset:10880
	ds_write_b128 v145, v[108:111] offset:11968
	ds_write_b128 v145, v[120:123] offset:13056
	ds_write_b128 v145, v[116:119] offset:14144
	ds_write_b128 v145, v[128:131] offset:15232
	ds_write_b128 v145, v[124:127] offset:16320
	s_waitcnt lgkmcnt(0)
	ds_read2_b32 v[156:157], v137 offset1:68
	ds_read2_b32 v[158:159], v137 offset0:136 offset1:204
	ds_read2_b32 v[160:161], v146 offset0:16 offset1:84
	ds_read2_b32 v[162:163], v146 offset0:152 offset1:220
	ds_read2_b32 v[164:165], v137 offset0:8 offset1:76
	ds_read2_b32 v[166:167], v137 offset0:144 offset1:212
	ds_read2_b32 v[168:169], v146 offset0:24 offset1:92
	ds_read2_b32 v[170:171], v146 offset0:160 offset1:228
	v_add_u32_e32 v34, s4, v136
	s_waitcnt lgkmcnt(4)
	v_cvt_pk_bf16_f32 v150, v156, v157
	v_cvt_pk_bf16_f32 v151, v158, v159
	v_cvt_pk_bf16_f32 v152, v160, v161
	v_cvt_pk_bf16_f32 v153, v162, v163
	ds_read2_b32 v[156:157], v137 offset0:16 offset1:84
	ds_read2_b32 v[158:159], v137 offset0:152 offset1:220
	ds_read2_b32 v[160:161], v146 offset0:32 offset1:100
	ds_read2_b32 v[162:163], v146 offset0:168 offset1:236
	v_mad_i64_i32 v[154:155], s[52:53], s60, v34, 0
	s_ashr_i32 s51, s50, 31
	v_lshl_add_u64 v[154:155], v[154:155], 1, s[48:49]
	s_lshl_b64 s[52:53], s[50:51], 1
	v_lshl_add_u64 v[154:155], v[154:155], 0, s[52:53]
	v_mov_b32_e32 v135, v35
	v_lshl_add_u64 v[154:155], v[154:155], 0, v[134:135]
	global_store_dwordx4 v[154:155], v[150:153], off nt
	s_nop 1
	v_add_u32_e32 v34, s4, v138
	s_waitcnt lgkmcnt(4)
	v_cvt_pk_bf16_f32 v150, v164, v165
	v_cvt_pk_bf16_f32 v151, v166, v167
	v_cvt_pk_bf16_f32 v152, v168, v169
	v_cvt_pk_bf16_f32 v153, v170, v171
	ds_read2_b32 v[164:165], v137 offset0:24 offset1:92
	ds_read2_b32 v[166:167], v137 offset0:160 offset1:228
	ds_read2_b32 v[168:169], v146 offset0:40 offset1:108
	ds_read2_b32 v[170:171], v146 offset0:176 offset1:244
	v_mad_i64_i32 v[154:155], s[54:55], s60, v34, 0
	v_lshl_add_u64 v[154:155], v[154:155], 1, s[48:49]
	v_lshl_add_u64 v[154:155], v[154:155], 0, s[52:53]
	v_lshl_add_u64 v[154:155], v[154:155], 0, v[134:135]
	global_store_dwordx4 v[154:155], v[150:153], off nt
	s_nop 1
	v_add_u32_e32 v34, s4, v139
	s_waitcnt lgkmcnt(4)
	v_cvt_pk_bf16_f32 v150, v156, v157
	v_cvt_pk_bf16_f32 v151, v158, v159
	v_cvt_pk_bf16_f32 v152, v160, v161
	v_cvt_pk_bf16_f32 v153, v162, v163
	ds_read2_b32 v[156:157], v137 offset0:32 offset1:100
	ds_read2_b32 v[158:159], v137 offset0:168 offset1:236
	ds_read2_b32 v[160:161], v146 offset0:48 offset1:116
	ds_read2_b32 v[162:163], v146 offset0:184 offset1:252
	v_mad_i64_i32 v[154:155], s[54:55], s60, v34, 0
	v_lshl_add_u64 v[154:155], v[154:155], 1, s[48:49]
	v_lshl_add_u64 v[154:155], v[154:155], 0, s[52:53]
	v_lshl_add_u64 v[154:155], v[154:155], 0, v[134:135]
	global_store_dwordx4 v[154:155], v[150:153], off nt
	s_nop 1
	v_add_u32_e32 v34, s4, v140
	s_waitcnt lgkmcnt(4)
	v_cvt_pk_bf16_f32 v150, v164, v165
	v_cvt_pk_bf16_f32 v151, v166, v167
	v_cvt_pk_bf16_f32 v152, v168, v169
	v_cvt_pk_bf16_f32 v153, v170, v171
	ds_read2_b32 v[164:165], v137 offset0:40 offset1:108
	ds_read2_b32 v[166:167], v137 offset0:176 offset1:244
	ds_read2_b32 v[168:169], v146 offset0:56 offset1:124
	ds_read2_b32 v[170:171], v147 offset0:64 offset1:132
	v_mad_i64_i32 v[154:155], s[54:55], s60, v34, 0
	v_lshl_add_u64 v[154:155], v[154:155], 1, s[48:49]
	v_lshl_add_u64 v[154:155], v[154:155], 0, s[52:53]
	v_lshl_add_u64 v[154:155], v[154:155], 0, v[134:135]
	global_store_dwordx4 v[154:155], v[150:153], off nt
	s_nop 1
	v_add_u32_e32 v34, s4, v141
	s_waitcnt lgkmcnt(4)
	v_cvt_pk_bf16_f32 v150, v156, v157
	v_cvt_pk_bf16_f32 v151, v158, v159
	v_cvt_pk_bf16_f32 v152, v160, v161
	v_cvt_pk_bf16_f32 v153, v162, v163
	ds_read2_b32 v[156:157], v137 offset0:48 offset1:116
	ds_read2_b32 v[158:159], v137 offset0:184 offset1:252
	ds_read2_b32 v[160:161], v146 offset0:64 offset1:132
	ds_read2_b32 v[162:163], v147 offset0:72 offset1:140
	v_mad_i64_i32 v[154:155], s[54:55], s60, v34, 0
	v_lshl_add_u64 v[154:155], v[154:155], 1, s[48:49]
	v_lshl_add_u64 v[154:155], v[154:155], 0, s[52:53]
	v_lshl_add_u64 v[154:155], v[154:155], 0, v[134:135]
	global_store_dwordx4 v[154:155], v[150:153], off nt
	s_nop 1
	v_add_u32_e32 v34, s4, v142
	s_waitcnt lgkmcnt(4)
	v_cvt_pk_bf16_f32 v150, v164, v165
	v_cvt_pk_bf16_f32 v151, v166, v167
	v_cvt_pk_bf16_f32 v152, v168, v169
	v_cvt_pk_bf16_f32 v153, v170, v171
	ds_read2_b32 v[164:165], v137 offset0:56 offset1:124
	ds_read2_b32 v[166:167], v148 offset0:64 offset1:132
	ds_read2_b32 v[168:169], v146 offset0:72 offset1:140
	ds_read2_b32 v[170:171], v147 offset0:80 offset1:148
	v_mad_i64_i32 v[154:155], s[54:55], s60, v34, 0
	v_lshl_add_u64 v[154:155], v[154:155], 1, s[48:49]
	v_lshl_add_u64 v[154:155], v[154:155], 0, s[52:53]
	v_lshl_add_u64 v[154:155], v[154:155], 0, v[134:135]
	global_store_dwordx4 v[154:155], v[150:153], off nt
	s_nop 1
	v_add_u32_e32 v34, s4, v143
	s_waitcnt lgkmcnt(4)
	v_cvt_pk_bf16_f32 v150, v156, v157
	v_cvt_pk_bf16_f32 v151, v158, v159
	v_cvt_pk_bf16_f32 v152, v160, v161
	v_cvt_pk_bf16_f32 v153, v162, v163
	v_mad_i64_i32 v[154:155], s[54:55], s60, v34, 0
	v_lshl_add_u64 v[154:155], v[154:155], 1, s[48:49]
	v_lshl_add_u64 v[154:155], v[154:155], 0, s[52:53]
	v_lshl_add_u64 v[154:155], v[154:155], 0, v[134:135]
	global_store_dwordx4 v[154:155], v[150:153], off nt
	s_nop 1
	v_add_u32_e32 v34, s4, v144
	s_waitcnt lgkmcnt(0)
	v_cvt_pk_bf16_f32 v150, v164, v165
	v_cvt_pk_bf16_f32 v151, v166, v167
	v_cvt_pk_bf16_f32 v152, v168, v169
	v_cvt_pk_bf16_f32 v153, v170, v171
	v_mad_i64_i32 v[146:147], s[54:55], s60, v34, 0
	v_lshl_add_u64 v[146:147], v[146:147], 1, s[48:49]
	v_lshl_add_u64 v[146:147], v[146:147], 0, s[52:53]
	v_lshl_add_u64 v[146:147], v[146:147], 0, v[134:135]
	global_store_dwordx4 v[146:147], v[150:153], off nt
	s_waitcnt lgkmcnt(0)
	s_cmp_lt_i32 s61, 0
	s_cselect_b64 s[52:53], -1, 0

.LBB0_408:
	s_cmpk_lt_i32 s9, 0x1400
	s_cselect_b64 s[54:55], -1, 0
	s_and_b64 s[52:53], s[54:55], exec
	s_cselect_b32 s57, s9, -1
	s_cmp_lt_i32 s57, 0
	s_cbranch_scc1 .LBB0_417
	s_cmpk_lt_u32 s57, 0x1000
	s_cbranch_scc1 .LBB0_415
	s_cmpk_gt_u32 s57, 0x13ff
	s_mov_b64 s[50:51], -1
	s_cbranch_scc0 .LBB0_413
	s_andn2_b64 vcc, exec, s[54:55]
	s_cbranch_vccnz .LBB0_431
	s_add_i32 s4, s9, 0xffffec00
	s_movk_i32 s60, 0x800
	s_movk_i32 s7, 0x2000
	s_mov_b64 s[48:49], s[18:19]
	s_mov_b64 s[52:53], s[16:17]
	s_mov_b64 s[50:51], 0

.LBB0_417:
	s_waitcnt vmcnt(15)
	ds_write_b128 v145, v[2:5]
	s_waitcnt vmcnt(14)
	ds_write_b128 v145, v[6:9] offset:1088
	s_waitcnt vmcnt(13)
	ds_write_b128 v145, v[10:13] offset:2176
	s_waitcnt vmcnt(12)
	ds_write_b128 v145, v[14:17] offset:3264
	s_waitcnt vmcnt(11)
	ds_write_b128 v145, v[18:21] offset:4352
	s_waitcnt vmcnt(10)
	ds_write_b128 v145, v[22:25] offset:5440
	s_waitcnt vmcnt(9)
	ds_write_b128 v145, v[26:29] offset:6528
	s_waitcnt vmcnt(8)
	ds_write_b128 v145, v[30:33] offset:7616
	s_waitcnt vmcnt(7)
	ds_write_b128 v145, v[36:39] offset:8704
	s_waitcnt vmcnt(6)
	ds_write_b128 v145, v[40:43] offset:9792
	s_waitcnt vmcnt(5)
	ds_write_b128 v145, v[44:47] offset:10880
	s_waitcnt vmcnt(4)
	ds_write_b128 v145, v[48:51] offset:11968
	s_waitcnt vmcnt(3)
	ds_write_b128 v145, v[52:55] offset:13056
	s_waitcnt vmcnt(2)
	ds_write_b128 v145, v[56:59] offset:14144
	s_waitcnt vmcnt(1)
	ds_write_b128 v145, v[60:63] offset:15232
	s_waitcnt vmcnt(0)
	ds_write_b128 v145, v[64:67] offset:16320
	s_waitcnt lgkmcnt(0)
	v_add_u32_e32 v172, 0x400, v137
	v_add_u32_e32 v173, 0x600, v137
	v_add_u32_e32 v174, 0x200, v137
	ds_read2_b32 v[156:157], v137 offset1:68
	ds_read2_b32 v[158:159], v137 offset0:136 offset1:204
	ds_read2_b32 v[160:161], v172 offset0:16 offset1:84
	ds_read2_b32 v[162:163], v172 offset0:152 offset1:220
	ds_read2_b32 v[164:165], v137 offset0:8 offset1:76
	ds_read2_b32 v[166:167], v137 offset0:144 offset1:212
	ds_read2_b32 v[168:169], v172 offset0:24 offset1:92
	ds_read2_b32 v[170:171], v172 offset0:160 offset1:228
	v_add_u32_e32 v146, 0x400, v137
	v_or_b32_e32 v34, s8, v136
	s_waitcnt lgkmcnt(4)
	v_cvt_pk_bf16_f32 v148, v156, v157
	v_cvt_pk_bf16_f32 v149, v158, v159
	v_cvt_pk_bf16_f32 v150, v160, v161
	v_cvt_pk_bf16_f32 v151, v162, v163
	ds_read2_b32 v[156:157], v137 offset0:16 offset1:84
	ds_read2_b32 v[158:159], v137 offset0:152 offset1:220
	ds_read2_b32 v[160:161], v172 offset0:32 offset1:100
	ds_read2_b32 v[162:163], v172 offset0:168 offset1:236
	v_mad_u64_u32 v[152:153], s[52:53], v34, s59, 0
	s_mov_b32 s7, s5
	v_lshl_add_u64 v[152:153], v[152:153], 1, s[0:1]
	s_lshl_b64 s[52:53], s[6:7], 1
	v_lshl_add_u64 v[152:153], v[152:153], 0, s[52:53]
	v_mov_b32_e32 v135, v35
	v_lshl_add_u64 v[152:153], v[152:153], 0, v[134:135]
	global_store_dwordx4 v[152:153], v[148:151], off nt
	s_nop 1
	v_or_b32_e32 v34, s8, v138
	s_waitcnt lgkmcnt(4)
	v_cvt_pk_bf16_f32 v148, v164, v165
	v_cvt_pk_bf16_f32 v149, v166, v167
	v_cvt_pk_bf16_f32 v150, v168, v169
	v_cvt_pk_bf16_f32 v151, v170, v171
	ds_read2_b32 v[164:165], v137 offset0:24 offset1:92
	ds_read2_b32 v[166:167], v137 offset0:160 offset1:228
	ds_read2_b32 v[168:169], v172 offset0:40 offset1:108
	ds_read2_b32 v[170:171], v172 offset0:176 offset1:244
	v_mad_u64_u32 v[152:153], s[54:55], v34, s59, 0
	v_lshl_add_u64 v[152:153], v[152:153], 1, s[0:1]
	v_lshl_add_u64 v[152:153], v[152:153], 0, s[52:53]
	v_lshl_add_u64 v[152:153], v[152:153], 0, v[134:135]
	global_store_dwordx4 v[152:153], v[148:151], off nt
	s_nop 1
	v_or_b32_e32 v34, s8, v139
	s_waitcnt lgkmcnt(4)
	v_cvt_pk_bf16_f32 v148, v156, v157
	v_cvt_pk_bf16_f32 v149, v158, v159
	v_cvt_pk_bf16_f32 v150, v160, v161
	v_cvt_pk_bf16_f32 v151, v162, v163
	ds_read2_b32 v[156:157], v137 offset0:32 offset1:100
	ds_read2_b32 v[158:159], v137 offset0:168 offset1:236
	ds_read2_b32 v[160:161], v172 offset0:48 offset1:116
	ds_read2_b32 v[162:163], v172 offset0:184 offset1:252
	v_mad_u64_u32 v[152:153], s[54:55], v34, s59, 0
	v_lshl_add_u64 v[152:153], v[152:153], 1, s[0:1]
	v_lshl_add_u64 v[152:153], v[152:153], 0, s[52:53]
	v_lshl_add_u64 v[152:153], v[152:153], 0, v[134:135]
	global_store_dwordx4 v[152:153], v[148:151], off nt
	s_nop 1
	v_or_b32_e32 v34, s8, v140
	s_waitcnt lgkmcnt(4)
	v_cvt_pk_bf16_f32 v148, v164, v165
	v_cvt_pk_bf16_f32 v149, v166, v167
	v_cvt_pk_bf16_f32 v150, v168, v169
	v_cvt_pk_bf16_f32 v151, v170, v171
	ds_read2_b32 v[164:165], v137 offset0:40 offset1:108
	ds_read2_b32 v[166:167], v137 offset0:176 offset1:244
	ds_read2_b32 v[168:169], v172 offset0:56 offset1:124
	ds_read2_b32 v[170:171], v173 offset0:64 offset1:132
	v_mad_u64_u32 v[152:153], s[54:55], v34, s59, 0
	v_lshl_add_u64 v[152:153], v[152:153], 1, s[0:1]
	v_lshl_add_u64 v[152:153], v[152:153], 0, s[52:53]
	v_lshl_add_u64 v[152:153], v[152:153], 0, v[134:135]
	global_store_dwordx4 v[152:153], v[148:151], off nt
	s_nop 1
	v_or_b32_e32 v34, s8, v141
	s_waitcnt lgkmcnt(4)
	v_cvt_pk_bf16_f32 v148, v156, v157
	v_cvt_pk_bf16_f32 v149, v158, v159
	v_cvt_pk_bf16_f32 v150, v160, v161
	v_cvt_pk_bf16_f32 v151, v162, v163
	ds_read2_b32 v[156:157], v137 offset0:48 offset1:116
	ds_read2_b32 v[158:159], v137 offset0:184 offset1:252
	ds_read2_b32 v[160:161], v172 offset0:64 offset1:132
	ds_read2_b32 v[162:163], v173 offset0:72 offset1:140
	v_mad_u64_u32 v[152:153], s[54:55], v34, s59, 0
	v_lshl_add_u64 v[152:153], v[152:153], 1, s[0:1]
	v_lshl_add_u64 v[152:153], v[152:153], 0, s[52:53]
	v_lshl_add_u64 v[152:153], v[152:153], 0, v[134:135]
	global_store_dwordx4 v[152:153], v[148:151], off nt
	s_nop 1
	v_add_u32_e32 v147, 0x600, v137
	v_or_b32_e32 v34, s8, v142
	s_waitcnt lgkmcnt(4)
	v_cvt_pk_bf16_f32 v148, v164, v165
	v_cvt_pk_bf16_f32 v149, v166, v167
	v_cvt_pk_bf16_f32 v150, v168, v169
	v_cvt_pk_bf16_f32 v151, v170, v171
	ds_read2_b32 v[164:165], v137 offset0:56 offset1:124
	ds_read2_b32 v[166:167], v174 offset0:64 offset1:132
	ds_read2_b32 v[168:169], v172 offset0:72 offset1:140
	ds_read2_b32 v[170:171], v173 offset0:80 offset1:148
	v_mad_u64_u32 v[152:153], s[54:55], v34, s59, 0
	v_lshl_add_u64 v[152:153], v[152:153], 1, s[0:1]
	v_lshl_add_u64 v[152:153], v[152:153], 0, s[52:53]
	v_lshl_add_u64 v[152:153], v[152:153], 0, v[134:135]
	global_store_dwordx4 v[152:153], v[148:151], off nt
	s_nop 1
	v_or_b32_e32 v34, s8, v143
	s_waitcnt lgkmcnt(4)
	v_cvt_pk_bf16_f32 v148, v156, v157
	v_cvt_pk_bf16_f32 v149, v158, v159
	v_cvt_pk_bf16_f32 v150, v160, v161
	v_cvt_pk_bf16_f32 v151, v162, v163
	v_mad_u64_u32 v[152:153], s[54:55], v34, s59, 0
	v_lshl_add_u64 v[152:153], v[152:153], 1, s[0:1]
	v_lshl_add_u64 v[152:153], v[152:153], 0, s[52:53]
	v_lshl_add_u64 v[152:153], v[152:153], 0, v[134:135]
	global_store_dwordx4 v[152:153], v[148:151], off nt
	s_nop 1
	v_or_b32_e32 v34, s8, v144
	v_add_u32_e32 v148, 0x200, v137
	s_waitcnt lgkmcnt(0)
	v_cvt_pk_bf16_f32 v150, v164, v165
	v_cvt_pk_bf16_f32 v151, v166, v167
	v_cvt_pk_bf16_f32 v152, v168, v169
	v_cvt_pk_bf16_f32 v153, v170, v171
	v_mad_u64_u32 v[154:155], s[54:55], v34, s59, 0
	v_lshl_add_u64 v[154:155], v[154:155], 1, s[0:1]
	v_lshl_add_u64 v[154:155], v[154:155], 0, s[52:53]
	v_lshl_add_u64 v[154:155], v[154:155], 0, v[134:135]
	global_store_dwordx4 v[154:155], v[150:153], off nt
	s_waitcnt lgkmcnt(0)
	s_mov_b64 s[52:53], -1
	s_cmp_lt_i32 s57, 0
	s_cbranch_scc1 .LBB0_401
	s_add_i32 s57, s9, 1
	s_cmp_lt_i32 s57, s56
	s_cbranch_scc1 .LBB0_424
	v_mov_b32_e32 v34, 0
	s_and_saveexec_b64 s[52:53], s[38:39]
	s_cbranch_execz .LBB0_423
	s_mov_b64 s[56:57], exec
	v_mbcnt_lo_u32_b32 v34, s56, 0
	v_mbcnt_hi_u32_b32 v34, s57, v34
	v_cmp_eq_u32_e32 vcc, 0, v34
	s_and_saveexec_b64 s[54:55], vcc
	s_cbranch_execz .LBB0_422
	s_bcnt1_i32_b64 s7, s[56:57]
	s_lshl_b32 s7, s7, 3
	v_mov_b32_e32 v135, s7
	global_atomic_add v135, v35, v135, s[10:11] offset:512 sc0

.LBB0_424:
	s_cmpk_lt_i32 s57, 0x1400
	s_cselect_b64 s[54:55], -1, 0
	s_and_b64 s[52:53], s[54:55], exec
	s_cselect_b32 s61, s57, -1
	s_cmp_lt_i32 s61, 0
	s_cbranch_scc1 .LBB0_400
	s_cmpk_lt_u32 s61, 0x1000
	s_cbranch_scc1 .LBB0_398
	s_cmpk_gt_u32 s61, 0x13ff
	s_mov_b64 s[6:7], -1
	s_cbranch_scc0 .LBB0_429
	s_andn2_b64 vcc, exec, s[54:55]
	s_cbranch_vccnz .LBB0_432
	s_add_i32 s8, s57, 0xffffec00
	s_movk_i32 s59, 0x800
	s_movk_i32 s51, 0x2000
	s_mov_b64 s[0:1], s[18:19]
	s_mov_b64 s[52:53], s[16:17]
	s_mov_b64 s[6:7], 0

.LBB0_1400:
	s_or_b64 exec, exec, s[0:1]
	v_readfirstlane_b32 s8, v2
	s_add_i32 s57, s8, 0x1400
	s_cmpk_lt_i32 s8, 0x2000
	s_cselect_b32 s14, s57, -1
	s_cmp_lt_i32 s14, 0
	s_cbranch_scc1 .LBB0_1452
	s_cmpk_gt_u32 s14, 0xfff
	s_mov_b64 s[6:7], -1
	s_cbranch_scc0 .LBB0_1410
	s_cmpk_gt_u32 s14, 0x13ff
	s_cbranch_scc0 .LBB0_1407
	s_lshl_b64 s[46:47], s[4:5], 26
	s_lshl_b64 s[48:49], s[4:5], 25
	s_cmpk_gt_u32 s14, 0x23ff
	s_cbranch_scc0 .LBB0_1405
	s_add_i32 s9, s14, 0xffffdc00
	s_add_u32 s10, s20, s46
	s_addc_u32 s11, s21, s47
	v_readlane_b32 s0, v252, 29
	s_add_u32 s0, s0, s48
	v_readlane_b32 s1, v252, 30
	s_addc_u32 s1, s1, s49
	s_mov_b64 s[6:7], 0

.LBB0_1412:
	s_lshr_b32 s6, s12, 6
	s_add_i32 s56, s8, 0x1408
	s_mulk_i32 s6, 0x4400
	s_lshr_b32 s8, s13, 6
	s_add_i32 s7, s6, 0
	s_ff1_i32_b32 s6, s8
	s_add_i32 s8, s8, -1
	s_and_b32 s8, s8, s9
	s_lshr_b32 s6, s9, s6
	s_lshl_b32 s8, s8, 6
	s_mov_b32 s9, s5
	s_lshl_b32 s6, s6, 6
	s_lshl_b64 s[14:15], s[8:9], 2
	v_lshlrev_b32_e32 v2, 2, v68
	s_waitcnt vmcnt(0)
	v_lshrrev_b32_e32 v133, 4, v68
	s_add_u32 s10, s10, s14
	v_and_b32_e32 v132, 60, v2
	v_or_b32_e32 v64, s6, v133
	s_addc_u32 s11, s11, s15
	v_lshlrev_b32_e32 v34, 2, v132
	v_lshl_add_u64 v[60:61], s[10:11], 0, v[34:35]
	v_or_b32_e32 v34, 32, v64
	v_mad_u64_u32 v[36:37], s[10:11], v34, s13, 0
	v_or_b32_e32 v34, 36, v64
	v_mad_u64_u32 v[38:39], s[10:11], v34, s13, 0
	v_or_b32_e32 v34, 40, v64
	v_mad_u64_u32 v[44:45], s[10:11], v34, s13, 0
	v_or_b32_e32 v34, 44, v64
	v_mad_u64_u32 v[46:47], s[10:11], v34, s13, 0
	v_or_b32_e32 v34, 48, v64
	v_mad_u64_u32 v[52:53], s[10:11], v34, s13, 0
	v_or_b32_e32 v34, 52, v64
	v_mad_u64_u32 v[54:55], s[10:11], v34, s13, 0
	v_or_b32_e32 v34, 56, v64
	v_or_b32_e32 v4, 4, v64
	v_or_b32_e32 v10, 8, v64
	v_or_b32_e32 v12, 12, v64
	v_or_b32_e32 v18, 16, v64
	v_or_b32_e32 v20, 20, v64
	v_or_b32_e32 v26, 24, v64
	v_or_b32_e32 v28, 28, v64
	v_mad_u64_u32 v[62:63], s[10:11], v34, s13, 0
	v_or_b32_e32 v34, 60, v64
	v_mad_u64_u32 v[2:3], s[10:11], v64, s13, 0
	v_mad_u64_u32 v[4:5], s[10:11], v4, s13, 0
	v_mad_u64_u32 v[10:11], s[10:11], v10, s13, 0
	v_mad_u64_u32 v[12:13], s[10:11], v12, s13, 0
	v_mad_u64_u32 v[18:19], s[10:11], v18, s13, 0
	v_mad_u64_u32 v[20:21], s[10:11], v20, s13, 0
	v_mad_u64_u32 v[26:27], s[10:11], v26, s13, 0
	v_mad_u64_u32 v[28:29], s[10:11], v28, s13, 0
	v_mad_u64_u32 v[64:65], s[10:11], v34, s13, 0
	v_lshl_add_u64 v[2:3], v[2:3], 2, v[60:61]
	v_lshl_add_u64 v[6:7], v[4:5], 2, v[60:61]
	v_lshl_add_u64 v[10:11], v[10:11], 2, v[60:61]
	v_lshl_add_u64 v[14:15], v[12:13], 2, v[60:61]
	v_lshl_add_u64 v[18:19], v[18:19], 2, v[60:61]
	v_lshl_add_u64 v[22:23], v[20:21], 2, v[60:61]
	v_lshl_add_u64 v[26:27], v[26:27], 2, v[60:61]
	v_lshl_add_u64 v[30:31], v[28:29], 2, v[60:61]
	v_lshl_add_u64 v[36:37], v[36:37], 2, v[60:61]
	v_lshl_add_u64 v[40:41], v[38:39], 2, v[60:61]
	v_lshl_add_u64 v[44:45], v[44:45], 2, v[60:61]
	v_lshl_add_u64 v[48:49], v[46:47], 2, v[60:61]
	v_lshl_add_u64 v[52:53], v[52:53], 2, v[60:61]
	v_lshl_add_u64 v[56:57], v[54:55], 2, v[60:61]
	v_lshl_add_u64 v[62:63], v[62:63], 2, v[60:61]
	v_lshl_add_u64 v[64:65], v[64:65], 2, v[60:61]
	global_load_dwordx4 v[2:5], v[2:3], off nt
	s_nop 0
	global_load_dwordx4 v[6:9], v[6:7], off nt
	s_nop 0
	global_load_dwordx4 v[10:13], v[10:11], off nt
	s_nop 0
	global_load_dwordx4 v[14:17], v[14:15], off nt
	s_nop 0
	global_load_dwordx4 v[18:21], v[18:19], off nt
	s_nop 0
	global_load_dwordx4 v[22:25], v[22:23], off nt
	s_nop 0
	global_load_dwordx4 v[26:29], v[26:27], off nt
	s_nop 0
	global_load_dwordx4 v[30:33], v[30:31], off nt
	s_nop 0
	global_load_dwordx4 v[36:39], v[36:37], off nt
	s_nop 0
	global_load_dwordx4 v[40:43], v[40:41], off nt
	s_nop 0
	global_load_dwordx4 v[44:47], v[44:45], off nt
	s_nop 0
	global_load_dwordx4 v[48:51], v[48:49], off nt
	s_nop 0
	global_load_dwordx4 v[52:55], v[52:53], off nt
	s_nop 0
	global_load_dwordx4 v[56:59], v[56:57], off nt
	s_nop 0
	global_load_dwordx4 v[60:63], v[62:63], off nt
	s_nop 0
	global_load_dwordx4 v[64:67], v[64:65], off nt
	v_lshlrev_b32_e32 v34, 4, v68
	s_lshl_b32 s10, s4, 6
	s_mov_b32 s11, s5
	v_and_b32_e32 v34, 0xf0, v34
	s_lshl_b64 s[10:11], s[10:11], 2
	v_add_u32_e32 v69, s7, v34
	v_lshlrev_b32_e32 v34, 3, v68
	s_add_u32 s10, s26, s10
	v_lshrrev_b32_e32 v136, 3, v68
	v_and_b32_e32 v34, 56, v34
	s_addc_u32 s11, s27, s11
	v_mul_u32_u24_e32 v68, 0x110, v34
	v_lshlrev_b32_e32 v71, 2, v136
	s_add_u32 s12, s20, s46
	v_readlane_b32 s64, v252, 7
	v_add3_u32 v137, s7, v68, v71
	s_addc_u32 s13, s21, s47
	v_readlane_b32 s7, v252, 29
	v_readlane_b32 s65, v252, 8
	v_readlane_b32 s66, v252, 9
	v_readlane_b32 s67, v252, 10
	v_readlane_b32 s68, v252, 11
	v_readlane_b32 s69, v252, 12
	v_readlane_b32 s70, v252, 13
	v_readlane_b32 s71, v252, 14
	v_readlane_b32 s72, v252, 15
	v_readlane_b32 s73, v252, 16
	v_readlane_b32 s74, v252, 17
	v_readlane_b32 s75, v252, 18
	s_add_u32 s14, s7, s48
	v_readlane_b32 s7, v252, 30
	v_readlane_b32 s76, v252, 19
	v_readlane_b32 s77, v252, 20
	v_readlane_b32 s78, v252, 21
	v_readlane_b32 s79, v252, 22
	s_mov_b64 s[64:65], s[68:69]
	s_addc_u32 s15, s7, s49
	s_mov_b64 s[66:67], s[70:71]
	s_mov_b64 s[68:69], s[72:73]
	s_mov_b64 s[70:71], s[74:75]
	s_mov_b64 s[72:73], s[76:77]
	s_mov_b64 s[74:75], s[78:79]
	s_add_u32 s16, s74, s46
	s_addc_u32 s17, s75, s47
	v_readlane_b32 s7, v252, 27
	s_add_u32 s18, s7, s48
	v_readlane_b32 s7, v252, 28
	s_addc_u32 s19, s7, s49
	s_lshl_b64 s[42:43], s[4:5], 24
	s_add_u32 s42, s72, s42
	s_addc_u32 s43, s73, s43
	s_lshl_b64 s[44:45], s[4:5], 23
	v_readlane_b32 s4, v252, 25
	s_add_u32 s44, s4, s44
	v_readlane_b32 s4, v252, 26
	s_addc_u32 s45, s4, s45
	s_add_u32 s46, s66, s46
	s_addc_u32 s47, s67, s47
	v_readlane_b32 s4, v252, 23
	v_mul_u32_u24_e32 v70, 0x110, v133
	s_add_u32 s48, s4, s48
	v_readlane_b32 s4, v252, 24
	v_readlane_b32 s76, v253, 43
	v_or_b32_e32 v138, 8, v136
	v_or_b32_e32 v139, 16, v136
	v_or_b32_e32 v140, 24, v136
	v_or_b32_e32 v141, 32, v136
	v_or_b32_e32 v142, 40, v136
	v_or_b32_e32 v143, 48, v136
	v_or_b32_e32 v144, 56, v136
	s_addc_u32 s49, s4, s49
	v_lshlrev_b32_e32 v134, 1, v34
	v_add_u32_e32 v145, v69, v70
	v_readlane_b32 s77, v253, 44
	v_readlane_b32 s78, v253, 45
	v_readlane_b32 s79, v253, 46
	v_readlane_b32 s74, v253, 47
	v_readlane_b32 s75, v253, 48
	s_movk_i32 s72, 0x4000
	s_mov_b32 s73, 0xa000
	s_branch .LBB0_1417

.LBB0_1415:
	ds_write_b128 v145, v[72:75]
	ds_write_b128 v145, v[68:71] offset:1088
	ds_write_b128 v145, v[80:83] offset:2176
	ds_write_b128 v145, v[76:79] offset:3264
	ds_write_b128 v145, v[88:91] offset:4352
	ds_write_b128 v145, v[84:87] offset:5440
	ds_write_b128 v145, v[96:99] offset:6528
	ds_write_b128 v145, v[92:95] offset:7616
	ds_write_b128 v145, v[104:107] offset:8704
	ds_write_b128 v145, v[100:103] offset:9792
	ds_write_b128 v145, v[112:115] offset:10880
	ds_write_b128 v145, v[108:111] offset:11968
	ds_write_b128 v145, v[120:123] offset:13056
	ds_write_b128 v145, v[116:119] offset:14144
	ds_write_b128 v145, v[128:131] offset:15232
	ds_write_b128 v145, v[124:127] offset:16320
	s_waitcnt lgkmcnt(0)
	ds_read2_b32 v[156:157], v137 offset1:68
	ds_read2_b32 v[158:159], v137 offset0:136 offset1:204
	ds_read2_b32 v[160:161], v146 offset0:16 offset1:84
	ds_read2_b32 v[162:163], v146 offset0:152 offset1:220
	ds_read2_b32 v[164:165], v137 offset0:8 offset1:76
	ds_read2_b32 v[166:167], v137 offset0:144 offset1:212
	ds_read2_b32 v[168:169], v146 offset0:24 offset1:92
	ds_read2_b32 v[170:171], v146 offset0:160 offset1:228
	v_add_u32_e32 v34, s4, v136
	s_waitcnt lgkmcnt(4)
	v_cvt_pk_bf16_f32 v150, v156, v157
	v_cvt_pk_bf16_f32 v151, v158, v159
	v_cvt_pk_bf16_f32 v152, v160, v161
	v_cvt_pk_bf16_f32 v153, v162, v163
	ds_read2_b32 v[156:157], v137 offset0:16 offset1:84
	ds_read2_b32 v[158:159], v137 offset0:152 offset1:220
	ds_read2_b32 v[160:161], v146 offset0:32 offset1:100
	ds_read2_b32 v[162:163], v146 offset0:168 offset1:236
	v_mad_i64_i32 v[154:155], s[54:55], s62, v34, 0
	s_ashr_i32 s53, s52, 31
	v_lshl_add_u64 v[154:155], v[154:155], 1, s[50:51]
	s_lshl_b64 s[54:55], s[52:53], 1
	v_lshl_add_u64 v[154:155], v[154:155], 0, s[54:55]
	v_mov_b32_e32 v135, v35
	v_lshl_add_u64 v[154:155], v[154:155], 0, v[134:135]
	global_store_dwordx4 v[154:155], v[150:153], off nt
	s_nop 1
	v_add_u32_e32 v34, s4, v138
	s_waitcnt lgkmcnt(4)
	v_cvt_pk_bf16_f32 v150, v164, v165
	v_cvt_pk_bf16_f32 v151, v166, v167
	v_cvt_pk_bf16_f32 v152, v168, v169
	v_cvt_pk_bf16_f32 v153, v170, v171
	ds_read2_b32 v[164:165], v137 offset0:24 offset1:92
	ds_read2_b32 v[166:167], v137 offset0:160 offset1:228
	ds_read2_b32 v[168:169], v146 offset0:40 offset1:108
	ds_read2_b32 v[170:171], v146 offset0:176 offset1:244
	v_mad_i64_i32 v[154:155], s[64:65], s62, v34, 0
	v_lshl_add_u64 v[154:155], v[154:155], 1, s[50:51]
	v_lshl_add_u64 v[154:155], v[154:155], 0, s[54:55]
	v_lshl_add_u64 v[154:155], v[154:155], 0, v[134:135]
	global_store_dwordx4 v[154:155], v[150:153], off nt
	s_nop 1
	v_add_u32_e32 v34, s4, v139
	s_waitcnt lgkmcnt(4)
	v_cvt_pk_bf16_f32 v150, v156, v157
	v_cvt_pk_bf16_f32 v151, v158, v159
	v_cvt_pk_bf16_f32 v152, v160, v161
	v_cvt_pk_bf16_f32 v153, v162, v163
	ds_read2_b32 v[156:157], v137 offset0:32 offset1:100
	ds_read2_b32 v[158:159], v137 offset0:168 offset1:236
	ds_read2_b32 v[160:161], v146 offset0:48 offset1:116
	ds_read2_b32 v[162:163], v146 offset0:184 offset1:252
	v_mad_i64_i32 v[154:155], s[64:65], s62, v34, 0
	v_lshl_add_u64 v[154:155], v[154:155], 1, s[50:51]
	v_lshl_add_u64 v[154:155], v[154:155], 0, s[54:55]
	v_lshl_add_u64 v[154:155], v[154:155], 0, v[134:135]
	global_store_dwordx4 v[154:155], v[150:153], off nt
	s_nop 1
	v_add_u32_e32 v34, s4, v140
	s_waitcnt lgkmcnt(4)
	v_cvt_pk_bf16_f32 v150, v164, v165
	v_cvt_pk_bf16_f32 v151, v166, v167
	v_cvt_pk_bf16_f32 v152, v168, v169
	v_cvt_pk_bf16_f32 v153, v170, v171
	ds_read2_b32 v[164:165], v137 offset0:40 offset1:108
	ds_read2_b32 v[166:167], v137 offset0:176 offset1:244
	ds_read2_b32 v[168:169], v146 offset0:56 offset1:124
	ds_read2_b32 v[170:171], v147 offset0:64 offset1:132
	v_mad_i64_i32 v[154:155], s[64:65], s62, v34, 0
	v_lshl_add_u64 v[154:155], v[154:155], 1, s[50:51]
	v_lshl_add_u64 v[154:155], v[154:155], 0, s[54:55]
	v_lshl_add_u64 v[154:155], v[154:155], 0, v[134:135]
	global_store_dwordx4 v[154:155], v[150:153], off nt
	s_nop 1
	v_add_u32_e32 v34, s4, v141
	s_waitcnt lgkmcnt(4)
	v_cvt_pk_bf16_f32 v150, v156, v157
	v_cvt_pk_bf16_f32 v151, v158, v159
	v_cvt_pk_bf16_f32 v152, v160, v161
	v_cvt_pk_bf16_f32 v153, v162, v163
	ds_read2_b32 v[156:157], v137 offset0:48 offset1:116
	ds_read2_b32 v[158:159], v137 offset0:184 offset1:252
	ds_read2_b32 v[160:161], v146 offset0:64 offset1:132
	ds_read2_b32 v[162:163], v147 offset0:72 offset1:140
	v_mad_i64_i32 v[154:155], s[64:65], s62, v34, 0
	v_lshl_add_u64 v[154:155], v[154:155], 1, s[50:51]
	v_lshl_add_u64 v[154:155], v[154:155], 0, s[54:55]
	v_lshl_add_u64 v[154:155], v[154:155], 0, v[134:135]
	global_store_dwordx4 v[154:155], v[150:153], off nt
	s_nop 1
	v_add_u32_e32 v34, s4, v142
	s_waitcnt lgkmcnt(4)
	v_cvt_pk_bf16_f32 v150, v164, v165
	v_cvt_pk_bf16_f32 v151, v166, v167
	v_cvt_pk_bf16_f32 v152, v168, v169
	v_cvt_pk_bf16_f32 v153, v170, v171
	ds_read2_b32 v[164:165], v137 offset0:56 offset1:124
	ds_read2_b32 v[166:167], v148 offset0:64 offset1:132
	ds_read2_b32 v[168:169], v146 offset0:72 offset1:140
	ds_read2_b32 v[170:171], v147 offset0:80 offset1:148
	v_mad_i64_i32 v[154:155], s[64:65], s62, v34, 0
	v_lshl_add_u64 v[154:155], v[154:155], 1, s[50:51]
	v_lshl_add_u64 v[154:155], v[154:155], 0, s[54:55]
	v_lshl_add_u64 v[154:155], v[154:155], 0, v[134:135]
	global_store_dwordx4 v[154:155], v[150:153], off nt
	s_nop 1
	v_add_u32_e32 v34, s4, v143
	s_waitcnt lgkmcnt(4)
	v_cvt_pk_bf16_f32 v150, v156, v157
	v_cvt_pk_bf16_f32 v151, v158, v159
	v_cvt_pk_bf16_f32 v152, v160, v161
	v_cvt_pk_bf16_f32 v153, v162, v163
	v_mad_i64_i32 v[154:155], s[64:65], s62, v34, 0
	v_lshl_add_u64 v[154:155], v[154:155], 1, s[50:51]
	v_lshl_add_u64 v[154:155], v[154:155], 0, s[54:55]
	v_lshl_add_u64 v[154:155], v[154:155], 0, v[134:135]
	global_store_dwordx4 v[154:155], v[150:153], off nt
	s_nop 1
	v_add_u32_e32 v34, s4, v144
	s_waitcnt lgkmcnt(0)
	v_cvt_pk_bf16_f32 v150, v164, v165
	v_cvt_pk_bf16_f32 v151, v166, v167
	v_cvt_pk_bf16_f32 v152, v168, v169
	v_cvt_pk_bf16_f32 v153, v170, v171
	v_mad_i64_i32 v[146:147], s[64:65], s62, v34, 0
	v_lshl_add_u64 v[146:147], v[146:147], 1, s[50:51]
	v_lshl_add_u64 v[146:147], v[146:147], 0, s[54:55]
	v_lshl_add_u64 v[146:147], v[146:147], 0, v[134:135]
	global_store_dwordx4 v[146:147], v[150:153], off nt
	s_waitcnt lgkmcnt(0)
	s_cmp_lt_i32 s58, 0
	s_cselect_b64 s[54:55], -1, 0

.LBB0_1422:
	s_or_b64 exec, exec, s[54:55]
	v_readfirstlane_b32 s7, v34
	s_add_i32 s9, s7, 0x1400
	s_add_i32 s56, s7, 0x1408

.LBB0_1434:
	s_waitcnt vmcnt(15)
	ds_write_b128 v145, v[2:5]
	s_waitcnt vmcnt(14)
	ds_write_b128 v145, v[6:9] offset:1088
	s_waitcnt vmcnt(13)
	ds_write_b128 v145, v[10:13] offset:2176
	s_waitcnt vmcnt(12)
	ds_write_b128 v145, v[14:17] offset:3264
	s_waitcnt vmcnt(11)
	ds_write_b128 v145, v[18:21] offset:4352
	s_waitcnt vmcnt(10)
	ds_write_b128 v145, v[22:25] offset:5440
	s_waitcnt vmcnt(9)
	ds_write_b128 v145, v[26:29] offset:6528
	s_waitcnt vmcnt(8)
	ds_write_b128 v145, v[30:33] offset:7616
	s_waitcnt vmcnt(7)
	ds_write_b128 v145, v[36:39] offset:8704
	s_waitcnt vmcnt(6)
	ds_write_b128 v145, v[40:43] offset:9792
	s_waitcnt vmcnt(5)
	ds_write_b128 v145, v[44:47] offset:10880
	s_waitcnt vmcnt(4)
	ds_write_b128 v145, v[48:51] offset:11968
	s_waitcnt vmcnt(3)
	ds_write_b128 v145, v[52:55] offset:13056
	s_waitcnt vmcnt(2)
	ds_write_b128 v145, v[56:59] offset:14144
	s_waitcnt vmcnt(1)
	ds_write_b128 v145, v[60:63] offset:15232
	s_waitcnt vmcnt(0)
	ds_write_b128 v145, v[64:67] offset:16320
	s_waitcnt lgkmcnt(0)
	v_add_u32_e32 v172, 0x400, v137
	v_add_u32_e32 v173, 0x600, v137
	v_add_u32_e32 v174, 0x200, v137
	ds_read2_b32 v[156:157], v137 offset1:68
	ds_read2_b32 v[158:159], v137 offset0:136 offset1:204
	ds_read2_b32 v[160:161], v172 offset0:16 offset1:84
	ds_read2_b32 v[162:163], v172 offset0:152 offset1:220
	ds_read2_b32 v[164:165], v137 offset0:8 offset1:76
	ds_read2_b32 v[166:167], v137 offset0:144 offset1:212
	ds_read2_b32 v[168:169], v172 offset0:24 offset1:92
	ds_read2_b32 v[170:171], v172 offset0:160 offset1:228
	v_add_u32_e32 v146, 0x400, v137
	v_or_b32_e32 v34, s8, v136
	s_waitcnt lgkmcnt(4)
	v_cvt_pk_bf16_f32 v148, v156, v157
	v_cvt_pk_bf16_f32 v149, v158, v159
	v_cvt_pk_bf16_f32 v150, v160, v161
	v_cvt_pk_bf16_f32 v151, v162, v163
	ds_read2_b32 v[156:157], v137 offset0:16 offset1:84
	ds_read2_b32 v[158:159], v137 offset0:152 offset1:220
	ds_read2_b32 v[160:161], v172 offset0:32 offset1:100
	ds_read2_b32 v[162:163], v172 offset0:168 offset1:236
	v_mad_u64_u32 v[152:153], s[54:55], v34, s61, 0
	s_mov_b32 s7, s5
	v_lshl_add_u64 v[152:153], v[152:153], 1, s[0:1]
	s_lshl_b64 s[54:55], s[6:7], 1
	v_lshl_add_u64 v[152:153], v[152:153], 0, s[54:55]
	v_mov_b32_e32 v135, v35
	v_lshl_add_u64 v[152:153], v[152:153], 0, v[134:135]
	global_store_dwordx4 v[152:153], v[148:151], off nt
	s_nop 1
	v_or_b32_e32 v34, s8, v138
	s_waitcnt lgkmcnt(4)
	v_cvt_pk_bf16_f32 v148, v164, v165
	v_cvt_pk_bf16_f32 v149, v166, v167
	v_cvt_pk_bf16_f32 v150, v168, v169
	v_cvt_pk_bf16_f32 v151, v170, v171
	ds_read2_b32 v[164:165], v137 offset0:24 offset1:92
	ds_read2_b32 v[166:167], v137 offset0:160 offset1:228
	ds_read2_b32 v[168:169], v172 offset0:40 offset1:108
	ds_read2_b32 v[170:171], v172 offset0:176 offset1:244
	v_mad_u64_u32 v[152:153], s[58:59], v34, s61, 0
	v_lshl_add_u64 v[152:153], v[152:153], 1, s[0:1]
	v_lshl_add_u64 v[152:153], v[152:153], 0, s[54:55]
	v_lshl_add_u64 v[152:153], v[152:153], 0, v[134:135]
	global_store_dwordx4 v[152:153], v[148:151], off nt
	s_nop 1
	v_or_b32_e32 v34, s8, v139
	s_waitcnt lgkmcnt(4)
	v_cvt_pk_bf16_f32 v148, v156, v157
	v_cvt_pk_bf16_f32 v149, v158, v159
	v_cvt_pk_bf16_f32 v150, v160, v161
	v_cvt_pk_bf16_f32 v151, v162, v163
	ds_read2_b32 v[156:157], v137 offset0:32 offset1:100
	ds_read2_b32 v[158:159], v137 offset0:168 offset1:236
	ds_read2_b32 v[160:161], v172 offset0:48 offset1:116
	ds_read2_b32 v[162:163], v172 offset0:184 offset1:252
	v_mad_u64_u32 v[152:153], s[58:59], v34, s61, 0
	v_lshl_add_u64 v[152:153], v[152:153], 1, s[0:1]
	v_lshl_add_u64 v[152:153], v[152:153], 0, s[54:55]
	v_lshl_add_u64 v[152:153], v[152:153], 0, v[134:135]
	global_store_dwordx4 v[152:153], v[148:151], off nt
	s_nop 1
	v_or_b32_e32 v34, s8, v140
	s_waitcnt lgkmcnt(4)
	v_cvt_pk_bf16_f32 v148, v164, v165
	v_cvt_pk_bf16_f32 v149, v166, v167
	v_cvt_pk_bf16_f32 v150, v168, v169
	v_cvt_pk_bf16_f32 v151, v170, v171
	ds_read2_b32 v[164:165], v137 offset0:40 offset1:108
	ds_read2_b32 v[166:167], v137 offset0:176 offset1:244
	ds_read2_b32 v[168:169], v172 offset0:56 offset1:124
	ds_read2_b32 v[170:171], v173 offset0:64 offset1:132
	v_mad_u64_u32 v[152:153], s[58:59], v34, s61, 0
	v_lshl_add_u64 v[152:153], v[152:153], 1, s[0:1]
	v_lshl_add_u64 v[152:153], v[152:153], 0, s[54:55]
	v_lshl_add_u64 v[152:153], v[152:153], 0, v[134:135]
	global_store_dwordx4 v[152:153], v[148:151], off nt
	s_nop 1
	v_or_b32_e32 v34, s8, v141
	s_waitcnt lgkmcnt(4)
	v_cvt_pk_bf16_f32 v148, v156, v157
	v_cvt_pk_bf16_f32 v149, v158, v159
	v_cvt_pk_bf16_f32 v150, v160, v161
	v_cvt_pk_bf16_f32 v151, v162, v163
	ds_read2_b32 v[156:157], v137 offset0:48 offset1:116
	ds_read2_b32 v[158:159], v137 offset0:184 offset1:252
	ds_read2_b32 v[160:161], v172 offset0:64 offset1:132
	ds_read2_b32 v[162:163], v173 offset0:72 offset1:140
	v_mad_u64_u32 v[152:153], s[58:59], v34, s61, 0
	v_lshl_add_u64 v[152:153], v[152:153], 1, s[0:1]
	v_lshl_add_u64 v[152:153], v[152:153], 0, s[54:55]
	v_lshl_add_u64 v[152:153], v[152:153], 0, v[134:135]
	global_store_dwordx4 v[152:153], v[148:151], off nt
	s_nop 1
	v_add_u32_e32 v147, 0x600, v137
	v_or_b32_e32 v34, s8, v142
	s_waitcnt lgkmcnt(4)
	v_cvt_pk_bf16_f32 v148, v164, v165
	v_cvt_pk_bf16_f32 v149, v166, v167
	v_cvt_pk_bf16_f32 v150, v168, v169
	v_cvt_pk_bf16_f32 v151, v170, v171
	ds_read2_b32 v[164:165], v137 offset0:56 offset1:124
	ds_read2_b32 v[166:167], v174 offset0:64 offset1:132
	ds_read2_b32 v[168:169], v172 offset0:72 offset1:140
	ds_read2_b32 v[170:171], v173 offset0:80 offset1:148
	v_mad_u64_u32 v[152:153], s[58:59], v34, s61, 0
	v_lshl_add_u64 v[152:153], v[152:153], 1, s[0:1]
	v_lshl_add_u64 v[152:153], v[152:153], 0, s[54:55]
	v_lshl_add_u64 v[152:153], v[152:153], 0, v[134:135]
	global_store_dwordx4 v[152:153], v[148:151], off nt
	s_nop 1
	v_or_b32_e32 v34, s8, v143
	s_waitcnt lgkmcnt(4)
	v_cvt_pk_bf16_f32 v148, v156, v157
	v_cvt_pk_bf16_f32 v149, v158, v159
	v_cvt_pk_bf16_f32 v150, v160, v161
	v_cvt_pk_bf16_f32 v151, v162, v163
	v_mad_u64_u32 v[152:153], s[58:59], v34, s61, 0
	v_lshl_add_u64 v[152:153], v[152:153], 1, s[0:1]
	v_lshl_add_u64 v[152:153], v[152:153], 0, s[54:55]
	v_lshl_add_u64 v[152:153], v[152:153], 0, v[134:135]
	global_store_dwordx4 v[152:153], v[148:151], off nt
	s_nop 1
	v_or_b32_e32 v34, s8, v144
	v_add_u32_e32 v148, 0x200, v137
	s_waitcnt lgkmcnt(0)
	v_cvt_pk_bf16_f32 v150, v164, v165
	v_cvt_pk_bf16_f32 v151, v166, v167
	v_cvt_pk_bf16_f32 v152, v168, v169
	v_cvt_pk_bf16_f32 v153, v170, v171
	v_mad_u64_u32 v[154:155], s[58:59], v34, s61, 0
	v_lshl_add_u64 v[154:155], v[154:155], 1, s[0:1]
	v_lshl_add_u64 v[154:155], v[154:155], 0, s[54:55]
	v_lshl_add_u64 v[154:155], v[154:155], 0, v[134:135]
	global_store_dwordx4 v[154:155], v[150:153], off nt
	s_waitcnt lgkmcnt(0)
	s_mov_b64 s[54:55], -1
	s_cmp_lt_i32 s57, 0
	s_cbranch_scc1 .LBB0_1416
	s_add_i32 s57, s9, 1
	s_cmp_lt_i32 s57, s56
	s_cbranch_scc1 .LBB0_1441
	v_mov_b32_e32 v34, 0
	s_and_saveexec_b64 s[54:55], s[40:41]
	s_cbranch_execz .LBB0_1440
	s_mov_b64 s[58:59], exec
	v_mbcnt_lo_u32_b32 v34, s58, 0
	v_mbcnt_hi_u32_b32 v34, s59, v34
	v_cmp_eq_u32_e32 vcc, 0, v34
	s_and_saveexec_b64 s[56:57], vcc
	s_cbranch_execz .LBB0_1439
	s_bcnt1_i32_b64 s7, s[58:59]
	s_lshl_b32 s7, s7, 3
	v_mov_b32_e32 v135, s7
	global_atomic_add v135, v35, v135, s[10:11] offset:576 sc0

.LBB0_1440:
	s_or_b64 exec, exec, s[54:55]
	v_readfirstlane_b32 s7, v34
	s_add_i32 s57, s7, 0x1400
	s_add_i32 s56, s7, 0x1408
